# GLA-C output tail: the four g_gla_o slices loaded once per phase instead of four serialized load+vmcnt(0) round trips per unit
# baseline (speedup 1.0000x reference)
.LBB0_917:
	v_lshrrev_b32_e32 v37, 3, v79
	s_and_b32 s3, s2, 3
	v_lshrrev_b32_e32 v34, 2, v79
	v_and_b32_e32 v36, 2, v37
	v_and_b32_e32 v35, 11, v34
	v_lshl_or_b32 v36, s3, 2, v36
	v_bfe_u32 v38, v28, 1, 1
	v_or_b32_e32 v39, v36, v38
	v_lshlrev_b32_e32 v40, 8, v35
	v_and_b32_e32 v41, 12, v28
	v_lshrrev_b32_e32 v35, 2, v35
	v_bitop3_b32 v35, v35, v39, v41 bitop3:0x36
	v_lshlrev_b32_e32 v35, 4, v35
	v_or_b32_e32 v34, 4, v34
	v_add3_u32 v40, 0, v35, v40
	v_lshlrev_b32_e32 v35, 8, v34
	v_lshrrev_b32_e32 v34, 2, v34
	v_bitop3_b32 v34, v34, v39, v41 bitop3:0x36
	v_lshlrev_b32_e32 v34, 4, v34
	v_add3_u32 v43, 0, v34, v35
	v_bfe_u32 v34, v79, 2, 2
	v_and_b32_e32 v35, 4, v37
	v_readlane_b32 s0, v253, 19
	v_lshrrev_b32_e32 v29, 5, v79
	v_or_b32_e32 v44, v35, v34
	v_or_b32_e32 v35, 8, v35
	v_readlane_b32 s1, v253, 20
	v_or_b32_e32 v45, v29, v41
	v_or_b32_e32 v34, v35, v34
	v_lshrrev_b32_e32 v35, 2, v35
	s_load_dword s0, s[0:1], 0x10
	v_bitop3_b32 v36, v36, v45, v38 bitop3:0x36
	v_bitop3_b32 v35, v35, v39, v41 bitop3:0x36
	v_lshlrev_b32_e32 v44, 8, v44
	v_lshlrev_b32_e32 v36, 4, v36
	v_lshlrev_b32_e32 v34, 8, v34
	v_lshlrev_b32_e32 v35, 4, v35
	v_lshlrev_b32_e32 v41, 2, v26
	v_add3_u32 v108, 0, v36, v44
	v_add3_u32 v109, 0, v35, v34
	v_and_b32_e32 v34, 12, v41
	v_bfe_u32 v35, v28, 2, 2
	v_or_b32_e32 v36, 2, v29
	v_bitop3_b32 v45, v34, v36, v35 bitop3:0x36
	v_or_b32_e32 v36, 4, v29
	v_bitop3_b32 v46, v34, v36, v35 bitop3:0x36
	v_or_b32_e32 v36, 6, v29
	s_waitcnt lgkmcnt(0)
	s_lshr_b32 s0, s0, 16
	v_bitop3_b32 v47, v34, v36, v35 bitop3:0x36
	v_or_b32_e32 v36, 8, v29
	s_ashr_i32 s4, s2, 2
	s_and_b32 s0, s0, 0xffff
	v_lshlrev_b32_e32 v39, 8, v26
	v_bitop3_b32 v36, v34, v36, v35 bitop3:0x36
	s_cmp_lg_u32 s0, 0
	v_lshl_or_b32 v48, v36, 4, v39
	v_or_b32_e32 v36, 10, v29
	s_cselect_b64 s[0:1], -1, 0
	v_bitop3_b32 v36, v34, v36, v35 bitop3:0x36
	s_cmp_lg_u64 s[0:1], 0
	v_lshl_or_b32 v49, v36, 4, v39
	v_or_b32_e32 v36, 12, v29
	s_addc_u32 s81, s33, 0
	s_lshl_b32 s5, s4, 13
	v_bitop3_b32 v44, v34, v29, v35 bitop3:0x36
	v_bitop3_b32 v36, v34, v36, v35 bitop3:0x36
	s_add_i32 s5, s5, 0
	v_lshl_or_b32 v50, v36, 4, v39
	v_or_b32_e32 v36, 14, v29
	v_lshl_add_u32 v44, v44, 4, s5
	v_lshl_add_u32 v45, v45, 4, s5
	v_lshl_add_u32 v46, v46, 4, s5
	v_lshl_add_u32 v47, v47, 4, s5
	s_lshl_b32 s5, s3, 8
	v_bitop3_b32 v34, v34, v36, v35 bitop3:0x36
	v_lshlrev_b32_e32 v36, 3, v28
	s_add_i32 s5, s5, 0
	s_lshl_b32 s10, s4, 7
	v_lshlrev_b32_e32 v42, 3, v79
	v_and_b32_e32 v78, 0x78, v36
	v_and_b32_e32 v80, 0xffffff80, v36
	v_ashrrev_i32_e32 v36, 3, v28
	s_movk_i32 s0, 0xffe0
	s_add_i32 s5, s5, s10
	v_and_b32_e32 v110, 8, v42
	v_lshlrev_b32_e32 v112, 3, v27
	s_waitcnt vmcnt(11)
	v_and_or_b32 v123, v36, s0, v26
	v_lshlrev_b32_e32 v36, 5, v27
	v_lshlrev_b32_e32 v42, 8, v27
	v_cmp_lt_i32_e64 s[0:1], 0, v27
	v_cmp_lt_i32_e64 s[6:7], 1, v27
	v_cmp_lt_i32_e64 s[8:9], 2, v27
	v_cmp_lt_i32_e64 s[12:13], 3, v27
	v_cmp_lt_i32_e64 s[14:15], 4, v27
	v_cmp_lt_i32_e64 s[16:17], 5, v27
	v_cmp_lt_i32_e64 s[18:19], 6, v27
	v_cmp_lt_i32_e64 s[20:21], 7, v27
	s_waitcnt vmcnt(10)
	v_add_u32_e32 v124, s5, v41
	v_lshlrev_b32_e32 v41, 11, v27
	v_lshlrev_b32_e32 v27, 1, v27
	v_or_b32_e32 v117, 4, v112
	v_or_b32_e32 v53, 8, v37
	v_and_b32_e32 v55, 2, v27
	v_bitop3_b32 v56, v27, v37, 2 bitop3:0x6c
	v_bitop3_b32 v27, v27, v53, 2 bitop3:0x6c
	v_bitop3_b32 v57, v55, v37, 4 bitop3:0x36
	v_bitop3_b32 v58, v55, v53, 4 bitop3:0x36
	v_bitop3_b32 v59, v55, v37, 8 bitop3:0x36
	v_bitop3_b32 v60, v55, v37, 8 bitop3:0x14
	v_bitop3_b32 v61, v55, v37, 12 bitop3:0x36
	v_bitop3_b32 v55, v55, v53, 12 bitop3:0x36
	v_lshrrev_b32_e32 v86, 2, v117
	v_lshlrev_b32_e32 v56, 4, v56
	v_lshlrev_b32_e32 v27, 4, v27
	v_lshlrev_b32_e32 v57, 4, v57
	v_lshlrev_b32_e32 v58, 4, v58
	v_lshlrev_b32_e32 v59, 4, v59
	v_lshlrev_b32_e32 v60, 4, v60
	v_lshlrev_b32_e32 v61, 4, v61
	v_lshlrev_b32_e32 v55, 4, v55
	v_bitop3_b32 v87, v86, v37, 3 bitop3:0x6c
	v_or_b32_e32 v118, 5, v112
	v_add3_u32 v56, 0, v56, v41
	v_add3_u32 v27, 0, v27, v41
	v_add3_u32 v57, 0, v57, v41
	v_add3_u32 v58, 0, v58, v41
	v_add3_u32 v59, 0, v59, v41
	v_add3_u32 v60, 0, v60, v41
	v_add3_u32 v61, 0, v61, v41
	v_add3_u32 v41, 0, v55, v41
	v_lshlrev_b32_e32 v55, 8, v117
	v_lshlrev_b32_e32 v87, 4, v87
	v_add3_u32 v91, 0, v87, v55
	v_bitop3_b32 v86, v86, v53, 3 bitop3:0x6c
	v_bfe_u32 v87, v118, 2, 2
	v_lshlrev_b32_e32 v86, 4, v86
	v_bitop3_b32 v88, v87, v37, 4 bitop3:0x36
	v_bitop3_b32 v87, v87, v53, 4 bitop3:0x36
	v_or_b32_e32 v119, 6, v112
	v_add3_u32 v55, 0, v86, v55
	v_lshlrev_b32_e32 v86, 8, v118
	v_lshlrev_b32_e32 v87, 4, v87
	v_lshlrev_b32_e32 v88, 4, v88
	v_add3_u32 v94, 0, v87, v86
	v_bfe_u32 v87, v119, 2, 2
	v_add3_u32 v93, 0, v88, v86
	v_bitop3_b32 v88, v87, v37, 8 bitop3:0x36
	v_bitop3_b32 v87, v87, v37, 8 bitop3:0x14
	v_or_b32_e32 v120, 7, v112
	v_lshlrev_b32_e32 v86, 8, v119
	v_lshlrev_b32_e32 v87, 4, v87
	v_ashrrev_i32_e32 v121, 4, v28
	v_add3_u32 v99, 0, v87, v86
	v_bfe_u32 v87, v120, 2, 2
	s_lshl_b32 s5, s3, 5
	v_lshlrev_b32_e32 v88, 4, v88
	v_bitop3_b32 v37, v87, v37, 12 bitop3:0x36
	v_bitop3_b32 v53, v87, v53, 12 bitop3:0x36
	v_lshlrev_b32_e32 v87, 2, v121
	v_add_u32_e32 v38, 0x200, v28
	v_and_b32_e32 v54, 15, v28
	v_add3_u32 v98, 0, v88, v86
	v_lshlrev_b32_e32 v86, 8, v120
	v_lshlrev_b32_e32 v37, 4, v37
	v_lshlrev_b32_e32 v53, 4, v53
	v_and_b32_e32 v87, 12, v87
	v_bfe_u32 v88, v121, 2, 2
	s_cmp_gt_i32 s4, -1
	v_ashrrev_i32_e32 v122, 4, v38
	v_add3_u32 v37, 0, v37, v86
	v_add3_u32 v53, 0, v53, v86
	v_lshlrev_b32_e32 v86, 8, v121
	v_bitop3_b32 v87, v87, v54, v88 bitop3:0x36
	s_cselect_b64 s[46:47], -1, 0
	s_cmp_lt_u32 s2, 4
	v_lshl_or_b32 v100, v87, 4, v86
	v_lshlrev_b32_e32 v87, 2, v122
	s_cselect_b64 s[10:11], -1, 0
	v_lshrrev_b32_e32 v38, 3, v28
	v_lshlrev_b32_e32 v28, 2, v29
	v_and_b32_e32 v87, 12, v87
	v_bfe_u32 v88, v122, 2, 2
	v_writelane_b32 v253, s10, 22
	v_lshlrev_b32_e32 v86, 8, v122
	v_bitop3_b32 v54, v87, v54, v88 bitop3:0x36
	v_writelane_b32 v253, s11, 23
	v_cmp_gt_u32_e64 s[10:11], v28, v26
	v_lshl_or_b32 v54, v54, 4, v86
	v_or_b32_e32 v86, 2, v28
	v_writelane_b32 v254, s10, 60
	s_cmp_gt_i32 s4, 0
	v_readlane_b32 s60, v253, 60
	v_writelane_b32 v254, s11, 61
	v_cmp_gt_u32_e64 s[10:11], v86, v26
	v_or_b32_e32 v86, 3, v28
	s_cselect_b64 s[50:51], -1, 0
	v_writelane_b32 v255, s10, 17
	s_cmp_eq_u32 s4, 1
	v_readlane_b32 s61, v253, 61
	v_writelane_b32 v255, s11, 18
	v_cmp_gt_u32_e64 s[10:11], v86, v26
	v_or_b32_e32 v86, 8, v28
	v_readlane_b32 s62, v253, 62
	v_writelane_b32 v255, s10, 19
	v_readlane_b32 s63, v253, 63
	v_readlane_b32 s64, v254, 0
	v_writelane_b32 v255, s11, 20
	v_cmp_gt_u32_e64 s[10:11], v86, v26
	v_or_b32_e32 v86, 9, v28
	v_readlane_b32 s65, v254, 1
	v_writelane_b32 v255, s10, 21
	v_readlane_b32 s66, v254, 2
	v_readlane_b32 s67, v254, 3
	v_writelane_b32 v255, s11, 22
	v_cmp_gt_u32_e64 s[10:11], v86, v26
	v_or_b32_e32 v86, 10, v28
	v_cmp_gt_u32_e64 s[38:39], v86, v26
	v_or_b32_e32 v86, 11, v28
	v_cmp_gt_u32_e64 s[48:49], v86, v26
	v_or_b32_e32 v86, 16, v28
	v_cmp_gt_u32_e64 s[82:83], v86, v26
	v_or_b32_e32 v86, 17, v28
	v_cmp_gt_u32_e64 s[84:85], v86, v26
	v_or_b32_e32 v86, 18, v28
	v_cmp_gt_u32_e64 s[92:93], v86, v26
	v_or_b32_e32 v86, 19, v28
	v_cmp_gt_u32_e64 s[34:35], v86, v26
	v_or_b32_e32 v86, 24, v28
	v_readlane_b32 s68, v254, 4
	v_readlane_b32 s69, v254, 5
	v_readlane_b32 s70, v254, 6
	v_readlane_b32 s71, v254, 7
	v_readlane_b32 s72, v254, 8
	v_readlane_b32 s73, v254, 9
	v_readlane_b32 s74, v254, 10
	v_readlane_b32 s75, v254, 11
	v_cmp_gt_u32_e64 s[36:37], v86, v26
	v_or_b32_e32 v86, 25, v28
	s_cselect_b64 s[58:59], -1, 0
	s_lshl_b32 s2, s3, 7
	s_mov_b64 s[24:25], s[68:69]
	v_cmp_gt_u32_e64 s[52:53], v86, v26
	v_or_b32_e32 v86, 26, v28
	v_readlane_b32 s60, v254, 44
	v_lshl_or_b32 v51, v34, 4, v39
	v_lshlrev_b32_e32 v34, 2, v79
	v_mov_b32_e32 v35, 0
	v_lshlrev_b32_e32 v52, 1, v79
	s_add_u32 s2, s24, s2
	v_cmp_gt_u32_e64 s[54:55], v86, v26
	v_or_b32_e32 v86, 27, v28
	v_readlane_b32 s70, v254, 54
	v_readlane_b32 s71, v254, 55
	v_add_u32_e32 v111, 0, v34
	v_and_b32_e32 v38, 4, v38
	v_and_b32_e32 v52, 14, v52
	s_addc_u32 s3, s25, 0
	v_cmp_gt_u32_e64 s[56:57], v86, v26
	v_lshl_add_u64 v[86:87], s[70:71], 0, v[34:35]
	v_lshlrev_b32_e32 v34, 4, v29
	v_readlane_b32 s31, v253, 21
	v_add_u32_e32 v82, 0x1000, v80
	v_and_b32_e32 v36, 0x60, v36
	v_lshl_or_b32 v125, s4, 5, v26
	v_writelane_b32 v255, s10, 23
	v_lshl_add_u64 v[88:89], s[2:3], 0, v[34:35]
	global_load_dwordx4 v[202:205], v[88:89], off
	global_load_dwordx4 v[206:209], v[88:89], off offset:32
	global_load_dwordx4 v[210:213], v[88:89], off offset:64
	global_load_dwordx4 v[214:217], v[88:89], off offset:96
	s_lshl_b32 s2, s31, 1
	v_lshlrev_b32_e32 v92, 1, v38
	v_add_u32_e32 v127, v111, v42
	s_waitcnt vmcnt(9)
	v_add_u32_e32 v128, v56, v52
	v_add_u32_e32 v129, v27, v52
	v_add_u32_e32 v130, v57, v52
	v_add_u32_e32 v131, v58, v52
	s_waitcnt vmcnt(8)
	v_add_u32_e32 v132, v59, v52
	v_add_u32_e32 v133, v60, v52
	v_add_u32_e32 v134, v61, v52
	v_add_u32_e32 v135, v41, v52
	v_add_u32_e32 v136, v91, v52
	v_add_u32_e32 v137, v55, v52
	v_add_u32_e32 v138, v93, v52
	v_add_u32_e32 v139, v94, v52
	v_add_u32_e32 v140, v98, v52
	v_add_u32_e32 v141, v99, v52
	v_add_u32_e32 v142, v37, v52
	v_add_u32_e32 v143, v53, v52
	v_add_u32_e32 v145, 0, v54
	v_add_u32_e32 v146, v40, v110
	v_add_u32_e32 v147, v43, v110
	v_add_u32_e32 v148, v44, v39
	v_add_u32_e32 v149, v45, v39
	v_add_u32_e32 v150, v46, v39
	v_add_u32_e32 v151, v47, v39
	v_add_u32_e32 v153, 0, v48
	v_add_u32_e32 v154, 0, v49
	v_add_u32_e32 v155, 0, v50
	v_add_u32_e32 v156, 0, v51
	v_mov_b64_e32 v[40:41], v[8:9]
	v_mov_b64_e32 v[44:45], v[4:5]
	s_waitcnt vmcnt(6)
	v_mov_b64_e32 v[48:49], v[16:17]
	v_mov_b64_e32 v[52:53], v[12:13]
	s_waitcnt vmcnt(4)
	v_mov_b64_e32 v[56:57], v[24:25]
	v_mov_b64_e32 v[60:61], v[20:21]
	s_mov_b32 s41, 0
	v_or_b32_e32 v113, 0x100, v79
	v_or_b32_e32 v114, 1, v112
	v_or_b32_e32 v115, 2, v112
	v_or_b32_e32 v116, 3, v112
	v_ashrrev_i32_e32 v81, 31, v80
	v_ashrrev_i32_e32 v83, 31, v82
	v_cmp_gt_u32_e64 s[22:23], 32, v79
	v_lshl_add_u32 v126, v125, 2, 0
	v_cmp_lt_u32_e64 s[26:27], v28, v26
	v_writelane_b32 v255, s11, 24
	s_lshl_b32 s24, s31, 6
	s_lshl_b32 s25, s81, 6
	s_add_i32 s28, s2, 0x7ffff000
	s_lshl_b32 s29, s81, 1
	s_movk_i32 s30, 0x1200
	v_lshlrev_b32_e32 v90, 1, v36
	v_add_u32_e32 v144, 0, v100
	v_mov_b32_e32 v152, 0x358637bd
	s_lshl_b32 s40, s5, 1
	v_lshlrev_b32_e32 v94, 1, v28
	s_waitcnt vmcnt(0)
	v_mov_b64_e32 v[36:37], v[84:85]
	v_mov_b64_e32 v[98:99], v[96:97]
	v_mov_b64_e32 v[100:101], v[104:105]
	v_mov_b64_e32 v[102:103], v[106:107]
	v_mov_b32_e32 v157, v74
	v_mov_b32_e32 v161, v75
	v_mov_b32_e32 v163, v76
	v_mov_b32_e32 v167, v77
	v_mov_b32_e32 v169, v95
	v_mov_b32_e32 v173, v181
	v_mov_b32_e32 v175, v182
	v_mov_b32_e32 v179, v183
	v_mov_b32_e32 v160, v73
	v_mov_b32_e32 v162, v71
	v_mov_b32_e32 v166, v69
	v_mov_b32_e32 v168, v67
	v_mov_b32_e32 v172, v66
	v_mov_b32_e32 v174, v64
	v_mov_b32_e32 v177, v62
	v_mov_b32_e32 v180, v32
	v_mov_b32_e32 v158, v72
	v_mov_b32_e32 v159, v70
	v_mov_b32_e32 v164, v68
	v_mov_b32_e32 v165, v63
	v_mov_b32_e32 v170, v65
	v_mov_b32_e32 v171, v31
	v_mov_b32_e32 v176, v33
	v_mov_b32_e32 v178, v30
	v_mov_b64_e32 v[38:39], v[6:7]
	v_mov_b64_e32 v[42:43], v[2:3]
	v_mov_b64_e32 v[46:47], v[14:15]
	v_mov_b64_e32 v[50:51], v[10:11]
	v_mov_b64_e32 v[54:55], v[22:23]
	v_mov_b64_e32 v[58:59], v[18:19]
	v_readlane_b32 s61, v254, 45
	v_readlane_b32 s62, v254, 46
	v_readlane_b32 s63, v254, 47
	v_readlane_b32 s64, v254, 48
	v_readlane_b32 s65, v254, 49
	v_readlane_b32 s66, v254, 50
	v_readlane_b32 s67, v254, 51
	v_readlane_b32 s68, v254, 52
	v_readlane_b32 s69, v254, 53
	v_readlane_b32 s72, v254, 56
	v_readlane_b32 s73, v254, 57
	v_readlane_b32 s74, v254, 58
	v_readlane_b32 s75, v254, 59
	s_branch .LBB0_919

.LBB0_957:
	s_nop 11
	v_mul_f32_e32 v18, v3, v3
	v_fmac_f32_e32 v18, v2, v2
	v_fmac_f32_e32 v18, v4, v4
	v_fmac_f32_e32 v18, v5, v5
	v_fmac_f32_e32 v18, v6, v6
	v_fmac_f32_e32 v18, v7, v7
	v_fmac_f32_e32 v18, v8, v8
	v_fmac_f32_e32 v18, v9, v9
	v_fmac_f32_e32 v18, v10, v10
	v_fmac_f32_e32 v18, v11, v11
	v_fmac_f32_e32 v18, v12, v12
	v_fmac_f32_e32 v18, v13, v13
	v_fmac_f32_e32 v18, v14, v14
	v_fmac_f32_e32 v18, v15, v15
	v_fmac_f32_e32 v18, v16, v16
	v_fmac_f32_e32 v18, v17, v17
	v_mov_b32_e32 v19, v18
	s_nop 1
	v_permlane32_swap_b32_e32 v18, v19
	s_and_saveexec_b64 s[2:3], s[22:23]
	v_add_f32_e32 v18, v18, v19
	ds_write_b32 v124, v18 offset:51200
	s_or_b64 exec, exec, s[2:3]
	s_waitcnt lgkmcnt(0)
	s_barrier
	v_cmp_gt_i32_e32 vcc, s42, v125
	s_and_saveexec_b64 s[2:3], vcc
	s_cbranch_execz .LBB0_918
	v_mov_b64_e32 v[22:23], v[202:203]
	v_mov_b64_e32 v[24:25], v[204:205]
	ds_read2st64_b32 v[18:19], v126 offset0:200 offset1:201
	s_mov_b32 s42, 0x800000
	v_and_b32_e32 v21, 0xffff0000, v106
	v_lshlrev_b32_e32 v28, 16, v106
	v_mul_f32_e32 v26, 0xbfb8aa3b, v28
	s_waitcnt lgkmcnt(0)
	v_add_f32_e32 v20, v18, v19
	ds_read2st64_b32 v[18:19], v126 offset0:202 offset1:203
	v_exp_f32_e32 v26, v26
	v_readlane_b32 s60, v254, 44
	v_readlane_b32 s61, v254, 45
	s_lshl_b32 s10, s10, 7
	s_waitcnt lgkmcnt(0)
	v_add_f32_e32 v18, v20, v18
	v_add_f32_e32 v18, v18, v19
	v_fmamk_f32 v18, v18, 0x3c000000, v152
	v_cmp_gt_f32_e32 vcc, s42, v18
	v_mul_f32_e32 v19, 0x4b800000, v18
	v_mov_b32_e32 v95, v35
	v_cndmask_b32_e32 v18, v18, v19, vcc
	v_rsq_f32_e32 v18, v18
	v_readlane_b32 s62, v254, 46
	v_readlane_b32 s63, v254, 47
	v_readlane_b32 s64, v254, 48
	v_mul_f32_e32 v19, 0x45800000, v18
	v_cndmask_b32_e32 v20, v18, v19, vcc
	v_pk_mul_f32 v[2:3], v[2:3], v[20:21] op_sel_hi:[1,0]
	v_add_u32_e32 v18, s11, v125
	v_ashrrev_i32_e32 v19, 31, v18
	v_lshlrev_b64 v[18:19], 11, v[18:19]
	v_lshl_add_u64 v[18:19], s[60:61], 0, v[18:19]
	s_ashr_i32 s11, s10, 31
	v_lshl_add_u64 v[18:19], s[10:11], 1, v[18:19]
	v_lshl_add_u64 v[18:19], v[18:19], 0, s[40:41]
	v_lshl_add_u64 v[18:19], v[18:19], 0, v[94:95]
	v_readlane_b32 s65, v254, 49
	v_readlane_b32 s66, v254, 50
	v_readlane_b32 s67, v254, 51
	v_readlane_b32 s68, v254, 52
	v_readlane_b32 s69, v254, 53
	v_readlane_b32 s70, v254, 54
	v_readlane_b32 s71, v254, 55
	v_readlane_b32 s72, v254, 56
	v_readlane_b32 s73, v254, 57
	v_readlane_b32 s74, v254, 58
	v_readlane_b32 s75, v254, 59
	s_waitcnt vmcnt(0)
	v_pk_mul_f32 v[2:3], v[22:23], v[2:3]
	v_mul_f32_e32 v22, 0xbfb8aa3b, v21
	v_exp_f32_e32 v27, v22
	s_nop 0
	v_pk_add_f32 v[22:23], v[26:27], 1.0 op_sel_hi:[1,0]
	s_nop 0
	v_div_scale_f32 v26, s[10:11], v23, v23, v21
	v_rcp_f32_e32 v27, v26
	s_nop 0
	v_fma_f32 v29, -v26, v27, 1.0
	v_fmac_f32_e32 v27, v29, v27
	v_div_scale_f32 v29, vcc, v21, v23, v21
	v_mul_f32_e32 v30, v29, v27
	v_fma_f32 v31, -v26, v30, v29
	v_fmac_f32_e32 v30, v31, v27
	v_fma_f32 v26, -v26, v30, v29
	v_div_fmas_f32 v26, v26, v27, v30
	v_div_fixup_f32 v23, v26, v23, v21
	v_div_scale_f32 v21, s[10:11], v22, v22, v28
	v_rcp_f32_e32 v26, v21
	s_nop 0
	v_fma_f32 v27, -v21, v26, 1.0
	v_fmac_f32_e32 v26, v27, v26
	v_div_scale_f32 v27, vcc, v28, v22, v28
	v_mul_f32_e32 v29, v27, v26
	v_fma_f32 v30, -v21, v29, v27
	v_fmac_f32_e32 v29, v30, v26
	v_fma_f32 v21, -v21, v29, v27
	v_div_fmas_f32 v21, v21, v26, v29
	v_div_fixup_f32 v22, v21, v22, v28
	v_and_b32_e32 v21, 0xffff0000, v107
	v_lshlrev_b32_e32 v26, 16, v107
	v_pk_mul_f32 v[2:3], v[22:23], v[2:3]
	v_mul_f32_e32 v22, 0xbfb8aa3b, v26
	v_mul_f32_e32 v23, 0xbfb8aa3b, v21
	v_exp_f32_e32 v22, v22
	v_exp_f32_e32 v23, v23
	v_pk_mul_f32 v[4:5], v[4:5], v[20:21] op_sel_hi:[1,0]
	v_cvt_pk_bf16_f32 v2, v2, v3
	v_pk_mul_f32 v[4:5], v[24:25], v[4:5]
	v_pk_add_f32 v[22:23], v[22:23], 1.0 op_sel_hi:[1,0]
	s_nop 0
	v_div_scale_f32 v24, s[10:11], v23, v23, v21
	v_rcp_f32_e32 v25, v24
	s_nop 0
	v_fma_f32 v27, -v24, v25, 1.0
	v_fmac_f32_e32 v25, v27, v25
	v_div_scale_f32 v27, vcc, v21, v23, v21
	v_mul_f32_e32 v28, v27, v25
	v_fma_f32 v29, -v24, v28, v27
	v_fmac_f32_e32 v28, v29, v25
	v_fma_f32 v24, -v24, v28, v27
	v_div_fmas_f32 v24, v24, v25, v28
	v_div_fixup_f32 v23, v24, v23, v21
	v_div_scale_f32 v21, s[10:11], v22, v22, v26
	v_rcp_f32_e32 v24, v21
	s_nop 0
	v_fma_f32 v25, -v21, v24, 1.0
	v_fmac_f32_e32 v24, v25, v24
	v_div_scale_f32 v25, vcc, v26, v22, v26
	v_mul_f32_e32 v27, v25, v24
	v_fma_f32 v28, -v21, v27, v25
	v_fmac_f32_e32 v27, v28, v24
	v_fma_f32 v21, -v21, v27, v25
	v_div_fmas_f32 v21, v21, v24, v27
	v_div_fixup_f32 v22, v21, v22, v26
	v_pk_mul_f32 v[4:5], v[22:23], v[4:5]
	v_and_b32_e32 v21, 0xffff0000, v104
	v_cvt_pk_bf16_f32 v3, v4, v5
	global_store_dwordx2 v[18:19], v[2:3], off
	s_nop 1
	v_mov_b64_e32 v[2:3], v[206:207]
	v_mov_b64_e32 v[4:5], v[208:209]
	v_lshlrev_b32_e32 v24, 16, v104
	v_pk_mul_f32 v[6:7], v[6:7], v[20:21] op_sel_hi:[1,0]
	v_mul_f32_e32 v22, 0xbfb8aa3b, v24
	v_exp_f32_e32 v22, v22
	v_pk_mul_f32 v[2:3], v[2:3], v[6:7]
	v_mul_f32_e32 v6, 0xbfb8aa3b, v21
	v_exp_f32_e32 v23, v6
	s_nop 0
	v_pk_add_f32 v[6:7], v[22:23], 1.0 op_sel_hi:[1,0]
	s_nop 0
	v_div_scale_f32 v22, s[10:11], v7, v7, v21
	v_rcp_f32_e32 v23, v22
	s_nop 0
	v_fma_f32 v25, -v22, v23, 1.0
	v_fmac_f32_e32 v23, v25, v23
	v_div_scale_f32 v25, vcc, v21, v7, v21
	v_mul_f32_e32 v26, v25, v23
	v_fma_f32 v27, -v22, v26, v25
	v_fmac_f32_e32 v26, v27, v23
	v_fma_f32 v22, -v22, v26, v25
	v_div_fmas_f32 v22, v22, v23, v26
	v_div_fixup_f32 v7, v22, v7, v21
	v_div_scale_f32 v21, s[10:11], v6, v6, v24
	v_rcp_f32_e32 v22, v21
	s_nop 0
	v_fma_f32 v23, -v21, v22, 1.0
	v_fmac_f32_e32 v22, v23, v22
	v_div_scale_f32 v23, vcc, v24, v6, v24
	v_mul_f32_e32 v25, v23, v22
	v_fma_f32 v26, -v21, v25, v23
	v_fmac_f32_e32 v25, v26, v22
	v_fma_f32 v21, -v21, v25, v23
	v_div_fmas_f32 v21, v21, v22, v25
	v_div_fixup_f32 v6, v21, v6, v24
	v_and_b32_e32 v21, 0xffff0000, v105
	v_lshlrev_b32_e32 v22, 16, v105
	v_pk_mul_f32 v[2:3], v[6:7], v[2:3]
	v_mul_f32_e32 v6, 0xbfb8aa3b, v22
	v_mul_f32_e32 v7, 0xbfb8aa3b, v21
	v_exp_f32_e32 v6, v6
	v_exp_f32_e32 v7, v7
	v_pk_mul_f32 v[8:9], v[8:9], v[20:21] op_sel_hi:[1,0]
	v_cvt_pk_bf16_f32 v2, v2, v3
	v_pk_mul_f32 v[4:5], v[4:5], v[8:9]
	v_pk_add_f32 v[6:7], v[6:7], 1.0 op_sel_hi:[1,0]
	s_nop 0
	v_div_scale_f32 v8, s[10:11], v7, v7, v21
	v_rcp_f32_e32 v9, v8
	s_nop 0
	v_fma_f32 v23, -v8, v9, 1.0
	v_fmac_f32_e32 v9, v23, v9
	v_div_scale_f32 v23, vcc, v21, v7, v21
	v_mul_f32_e32 v24, v23, v9
	v_fma_f32 v25, -v8, v24, v23
	v_fmac_f32_e32 v24, v25, v9
	v_fma_f32 v8, -v8, v24, v23
	v_div_fmas_f32 v8, v8, v9, v24
	v_div_fixup_f32 v7, v8, v7, v21
	v_div_scale_f32 v8, s[10:11], v6, v6, v22
	v_rcp_f32_e32 v9, v8
	s_nop 0
	v_fma_f32 v21, -v8, v9, 1.0
	v_fmac_f32_e32 v9, v21, v9
	v_div_scale_f32 v21, vcc, v22, v6, v22
	v_mul_f32_e32 v23, v21, v9
	v_fma_f32 v24, -v8, v23, v21
	v_fmac_f32_e32 v23, v24, v9
	v_fma_f32 v8, -v8, v23, v21
	v_div_fmas_f32 v8, v8, v9, v23
	v_div_fixup_f32 v6, v8, v6, v22
	v_pk_mul_f32 v[4:5], v[6:7], v[4:5]
	v_and_b32_e32 v21, 0xffff0000, v96
	v_cvt_pk_bf16_f32 v3, v4, v5
	global_store_dwordx2 v[18:19], v[2:3], off offset:16
	s_nop 1
	v_mov_b64_e32 v[2:3], v[210:211]
	v_mov_b64_e32 v[4:5], v[212:213]
	v_lshlrev_b32_e32 v22, 16, v96
	v_mul_f32_e32 v6, 0xbfb8aa3b, v22
	v_mul_f32_e32 v7, 0xbfb8aa3b, v21
	v_exp_f32_e32 v6, v6
	v_exp_f32_e32 v7, v7
	v_pk_mul_f32 v[8:9], v[10:11], v[20:21] op_sel_hi:[1,0]
	v_pk_add_f32 v[6:7], v[6:7], 1.0 op_sel_hi:[1,0]
	v_pk_mul_f32 v[2:3], v[2:3], v[8:9]
	v_div_scale_f32 v8, s[10:11], v7, v7, v21
	v_rcp_f32_e32 v9, v8
	s_nop 0
	v_fma_f32 v10, -v8, v9, 1.0
	v_fmac_f32_e32 v9, v10, v9
	v_div_scale_f32 v10, vcc, v21, v7, v21
	v_mul_f32_e32 v11, v10, v9
	v_fma_f32 v23, -v8, v11, v10
	v_fmac_f32_e32 v11, v23, v9
	v_fma_f32 v8, -v8, v11, v10
	v_div_fmas_f32 v8, v8, v9, v11
	v_div_fixup_f32 v7, v8, v7, v21
	v_div_scale_f32 v8, s[10:11], v6, v6, v22
	v_rcp_f32_e32 v9, v8
	s_nop 0
	v_fma_f32 v10, -v8, v9, 1.0
	v_fmac_f32_e32 v9, v10, v9
	v_div_scale_f32 v10, vcc, v22, v6, v22
	v_mul_f32_e32 v11, v10, v9
	v_fma_f32 v21, -v8, v11, v10
	v_fmac_f32_e32 v11, v21, v9
	v_fma_f32 v8, -v8, v11, v10
	v_div_fmas_f32 v8, v8, v9, v11
	v_div_fixup_f32 v6, v8, v6, v22
	v_and_b32_e32 v10, 0xffff0000, v97
	v_lshlrev_b32_e32 v11, 16, v97
	v_pk_mul_f32 v[2:3], v[6:7], v[2:3]
	v_mul_f32_e32 v6, 0xbfb8aa3b, v11
	v_mul_f32_e32 v7, 0xbfb8aa3b, v10
	v_exp_f32_e32 v6, v6
	v_exp_f32_e32 v7, v7
	v_pk_mul_f32 v[8:9], v[12:13], v[20:21] op_sel_hi:[1,0]
	v_cvt_pk_bf16_f32 v2, v2, v3
	v_pk_mul_f32 v[4:5], v[4:5], v[8:9]
	v_pk_add_f32 v[6:7], v[6:7], 1.0 op_sel_hi:[1,0]
	s_nop 0
	v_div_scale_f32 v8, s[10:11], v7, v7, v10
	v_rcp_f32_e32 v9, v8
	s_nop 0
	v_fma_f32 v12, -v8, v9, 1.0
	v_fmac_f32_e32 v9, v12, v9
	v_div_scale_f32 v12, vcc, v10, v7, v10
	v_mul_f32_e32 v13, v12, v9
	v_fma_f32 v21, -v8, v13, v12
	v_fmac_f32_e32 v13, v21, v9
	v_fma_f32 v8, -v8, v13, v12
	v_div_fmas_f32 v8, v8, v9, v13
	v_div_fixup_f32 v7, v8, v7, v10
	v_div_scale_f32 v8, s[10:11], v6, v6, v11
	v_rcp_f32_e32 v9, v8
	s_nop 0
	v_fma_f32 v10, -v8, v9, 1.0
	v_fmac_f32_e32 v9, v10, v9
	v_div_scale_f32 v10, vcc, v11, v6, v11
	v_mul_f32_e32 v12, v10, v9
	v_fma_f32 v13, -v8, v12, v10
	v_fmac_f32_e32 v12, v13, v9
	v_fma_f32 v8, -v8, v12, v10
	v_div_fmas_f32 v8, v8, v9, v12
	v_div_fixup_f32 v6, v8, v6, v11
	v_pk_mul_f32 v[4:5], v[6:7], v[4:5]
	v_and_b32_e32 v10, 0xffff0000, v84
	v_cvt_pk_bf16_f32 v3, v4, v5
	global_store_dwordx2 v[18:19], v[2:3], off offset:32
	s_nop 1
	v_mov_b64_e32 v[2:3], v[214:215]
	v_mov_b64_e32 v[4:5], v[216:217]
	v_lshlrev_b32_e32 v11, 16, v84
	v_mul_f32_e32 v6, 0xbfb8aa3b, v11
	v_mul_f32_e32 v7, 0xbfb8aa3b, v10
	v_exp_f32_e32 v6, v6
	v_exp_f32_e32 v7, v7
	v_pk_mul_f32 v[8:9], v[14:15], v[20:21] op_sel_hi:[1,0]
	v_pk_add_f32 v[6:7], v[6:7], 1.0 op_sel_hi:[1,0]
	v_pk_mul_f32 v[2:3], v[2:3], v[8:9]
	v_div_scale_f32 v8, s[10:11], v7, v7, v10
	v_rcp_f32_e32 v9, v8
	s_nop 0
	v_fma_f32 v12, -v8, v9, 1.0
	v_fmac_f32_e32 v9, v12, v9
	v_div_scale_f32 v12, vcc, v10, v7, v10
	v_mul_f32_e32 v13, v12, v9
	v_fma_f32 v14, -v8, v13, v12
	v_fmac_f32_e32 v13, v14, v9
	v_fma_f32 v8, -v8, v13, v12
	v_div_fmas_f32 v8, v8, v9, v13
	v_div_fixup_f32 v7, v8, v7, v10
	v_div_scale_f32 v8, s[10:11], v6, v6, v11
	v_rcp_f32_e32 v9, v8
	s_nop 0
	v_fma_f32 v10, -v8, v9, 1.0
	v_fmac_f32_e32 v9, v10, v9
	v_div_scale_f32 v10, vcc, v11, v6, v11
	v_mul_f32_e32 v12, v10, v9
	v_fma_f32 v13, -v8, v12, v10
	v_fmac_f32_e32 v12, v13, v9
	v_fma_f32 v8, -v8, v12, v10
	v_div_fmas_f32 v8, v8, v9, v12
	v_div_fixup_f32 v6, v8, v6, v11
	v_and_b32_e32 v10, 0xffff0000, v85
	v_lshlrev_b32_e32 v11, 16, v85
	v_pk_mul_f32 v[2:3], v[6:7], v[2:3]
	v_mul_f32_e32 v6, 0xbfb8aa3b, v11
	v_mul_f32_e32 v7, 0xbfb8aa3b, v10
	v_exp_f32_e32 v6, v6
	v_exp_f32_e32 v7, v7
	v_pk_mul_f32 v[8:9], v[16:17], v[20:21] op_sel_hi:[1,0]
	v_cvt_pk_bf16_f32 v2, v2, v3
	v_pk_mul_f32 v[4:5], v[4:5], v[8:9]
	v_pk_add_f32 v[6:7], v[6:7], 1.0 op_sel_hi:[1,0]
	s_nop 0
	v_div_scale_f32 v8, s[10:11], v7, v7, v10
	v_rcp_f32_e32 v9, v8
	s_nop 0
	v_fma_f32 v12, -v8, v9, 1.0
	v_fmac_f32_e32 v9, v12, v9
	v_div_scale_f32 v12, vcc, v10, v7, v10
	v_mul_f32_e32 v13, v12, v9
	v_fma_f32 v14, -v8, v13, v12
	v_fmac_f32_e32 v13, v14, v9
	v_fma_f32 v8, -v8, v13, v12
	v_div_fmas_f32 v8, v8, v9, v13
	v_div_fixup_f32 v7, v8, v7, v10
	v_div_scale_f32 v8, s[10:11], v6, v6, v11
	v_rcp_f32_e32 v9, v8
	s_nop 0
	v_fma_f32 v10, -v8, v9, 1.0
	v_fmac_f32_e32 v9, v10, v9
	v_div_scale_f32 v10, vcc, v11, v6, v11
	v_mul_f32_e32 v12, v10, v9
	v_fma_f32 v13, -v8, v12, v10
	v_fmac_f32_e32 v12, v13, v9
	v_fma_f32 v8, -v8, v12, v10
	v_div_fmas_f32 v8, v8, v9, v12
	v_div_fixup_f32 v6, v8, v6, v11
	v_pk_mul_f32 v[4:5], v[6:7], v[4:5]
	s_nop 0
	v_cvt_pk_bf16_f32 v3, v4, v5
	global_store_dwordx2 v[18:19], v[2:3], off offset:48
	s_nop 1
	s_branch .LBB0_918
